# prep part 2: loads issued at the tile loop top so they land while part 1 runs
# baseline (speedup 1.0000x reference)
; DI int otid() { int t = threadIdx.x & 255; asm volatile("" : "+v"(t)); return t; }
; DI int oidx(int i) { asm volatile("" : "+s"(i)); return i; }
; DI int VB() { return blockIdx.x * 2 + vhalf(); }
; DN void phase_prep(const Params& p, int l, char* smem) {
;   bfr* P = (bfr*)(p.ws + OFF_P);
;   bfr* AL = (bfr*)(p.ws + OFF_HO);
;   const float* rope = (const float*)(p.ws + OFF_ROPE);
;   const float* mu = p.in[oidx(10)] + (size_t)l * 2 * 1152;
;   const int tid = otid(), lane = tid & 63, w = tid >> 6;
;   for (int tile = VB(); tile < MR / 8; tile += NVB()) {
;     ...
;       const int tk = i / 112, gi = i - tk * 112;
;       const int m = m0 + tk, t = m % TT;
;       const bool da = gi < 64;
;       const int gq = gi - 64;
;       const bool isq = da ? (gi < 32) : (gq < 32);
;       const int col = da ? (1152 + 8 * gi) : (isq ? (2720 + 8 * gq) : (2976 + 8 * (gq - 32)));
;       const int dofs = da ? ((gi & 3) * 8) : ((gq & 7) * 8);
;       bfr* ptr = P + (size_t)m * PW + col;
;       float x[8], gs[8];
;       unpack8(*(const u32x4*)ptr, x);
;       load8f(da ? (p.in[oidx(21)] + (l * 2 + (isq ? 0 : 1)) * 32 + dofs) : (p.in[oidx(27)] + (l * 2 + (isq ? 0 : 1)) * 64 + dofs), gs);
.LBB0_268:
	v_readlane_b32 s99, v253, 13
	s_load_dwordx2 s[6:7], s[0:1], 0xa8
	s_load_dwordx2 s[10:11], s[0:1], 0x108
	s_nop 3
	s_lshl_b32 s99, s99, 8
	s_mul_i32 s18, s20, 0x1c72
	s_lshr_b32 s18, s18, 21
	s_mul_i32 s18, s18, 0x120
	s_sub_i32 s18, s20, s18
	s_cmpk_ge_i32 s18, 0x100
	s_cselect_b32 s98, 1, 0
	s_lshl_b32 s18, s18, 3
	s_cmp_eq_u32 s98, 1
	s_cselect_b32 s18, 0, s18
	s_mul_i32 s9, s18, 0x180
	s_waitcnt lgkmcnt(0)
	s_add_u32 s10, s10, 0x2abc000
	s_addc_u32 s11, s11, 0
	s_add_u32 s10, s10, s9
	s_addc_u32 s11, s11, 0
	s_load_dwordx2 s[8:9], s[0:1], 0xd8
	s_mul_i32 s18, s20, 0xcc00
	s_add_u32 s18, s84, s18
	s_addc_u32 s19, s85, 0
	s_waitcnt lgkmcnt(0)
; DI int oidx(int i) { asm volatile("" : "+s"(i)); return i; }
; DN void phase_prep(const Params& p, int l, char* smem) {
;     ...
;       const int tk = i / 112, gi = i - tk * 112;
;       const int m = m0 + tk, t = m % TT;
;       const bool da = gi < 64;
;       const int gq = gi - 64;
;       const bool isq = da ? (gi < 32) : (gq < 32);
;       const int col = da ? (1152 + 8 * gi) : (isq ? (2720 + 8 * gq) : (2976 + 8 * (gq - 32)));
;       const int dofs = da ? ((gi & 3) * 8) : ((gq & 7) * 8);
;       bfr* ptr = P + (size_t)m * PW + col;
;       float x[8], gs[8];
;       unpack8(*(const u32x4*)ptr, x);
;       load8f(da ? (p.in[oidx(21)] + (l * 2 + (isq ? 0 : 1)) * 32 + dofs) : (p.in[oidx(27)] + (l * 2 + (isq ? 0 : 1)) * 64 + dofs), gs);
;       float ss = 0.f;
; #pragma unroll
;       for (int e = 0; e < 8; ++e) ss += x[e] * x[e];
;       ss += dppf<0xB1>(ss); ss += dppf<0x4E>(ss);
;       const float ss8 = ss + dppf<0x141>(ss);
;       const float rstd = da ? rsqrtf(ss * (1.f / 32.f) + 1e-6f) : rsqrtf(ss8 * (1.f / 64.f) + 1e-6f);
;       float y[8];
; #pragma unroll
;       for (int e = 0; e < 8; ++e) y[e] = x[e] * rstd * gs[e];
;       float yp2[8], yp4[8];
; #pragma unroll
;       for (int e = 0; e < 8; ++e) { yp2[e] = __shfl_xor(y[e], 2); yp4[e] = __shfl_xor(y[e], 4); }
;       if (t < TL) {
;         const int idx0 = da ? ((gi & 1) * 8) : ((gq & 3) * 8);
;         const bool first = da ? ((gi & 2) == 0) : ((gq & 4) == 0);
;         float cs[8], sn[8];
;         load8f(rope + t * 96 + (da ? 0 : 32) + idx0, cs);
;         load8f(rope + t * 96 + (da ? 16 : 64) + idx0, sn);
	v_mov_b32_e32 v0, v183
	v_mul_u32_u24_e32 v1, 0x925, v0
	v_lshrrev_b32_e32 v1, 18, v1
	v_mul_u32_u24_e32 v2, 0x70, v1
	v_sub_u32_e32 v2, v0, v2
	v_cmp_gt_u32_e32 vcc, 64, v2
	v_mov_b32_e32 v3, 0x1140
	v_mov_b32_e32 v4, 0x900
	v_cndmask_b32_e32 v3, v3, v4, vcc
	v_lshl_add_u32 v3, v2, 4, v3
	v_mul_u32_u24_e32 v4, 0x1980, v1
	v_add_u32_e32 v154, v3, v4
	global_load_dwordx4 v[40:43], v154, s[18:19]
	v_and_b32_e32 v5, 3, v2
	v_lshlrev_b32_e32 v5, 5, v5
	v_and_b32_e32 v6, 32, v2
	v_lshl_add_u32 v5, v6, 2, v5
	v_add_u32_e32 v5, s99, v5
	v_subrev_u32_e32 v6, 64, v2
	v_and_b32_e32 v7, 7, v6
	v_lshlrev_b32_e32 v7, 5, v7
	v_and_b32_e32 v8, 32, v6
	v_lshl_add_u32 v7, v8, 3, v7
	v_lshl_add_u32 v7, s99, 1, v7
	v_cndmask_b32_e32 v12, v7, v5, vcc
	v_mov_b32_e32 v8, s8
	v_mov_b32_e32 v9, s9
	v_mov_b32_e32 v10, s6
	v_mov_b32_e32 v11, s7
	v_cndmask_b32_e32 v8, v8, v10, vcc
	v_cndmask_b32_e32 v9, v9, v11, vcc
	v_mov_b32_e32 v13, 0
	v_lshl_add_u64 v[8:9], v[8:9], 0, v[12:13]
	global_load_dwordx4 v[120:123], v[8:9], off
	global_load_dwordx4 v[124:127], v[8:9], off offset:16
	v_and_b32_e32 v5, 1, v2
	v_and_b32_e32 v6, 3, v2
	v_cndmask_b32_e32 v5, v6, v5, vcc
	v_lshlrev_b32_e32 v5, 5, v5
	v_mov_b32_e32 v6, 0x80
	v_cndmask_b32_e64 v6, v6, 0, vcc
	v_add_u32_e32 v5, v5, v6
	v_mul_u32_u24_e32 v6, 0x180, v1
	v_add_u32_e32 v5, v5, v6
	v_mov_b32_e32 v6, 0x80
	v_mov_b32_e32 v7, 0x40
	v_cndmask_b32_e32 v6, v6, v7, vcc
	v_add_u32_e32 v6, v5, v6
	global_load_dwordx4 v[56:59], v5, s[10:11]
	global_load_dwordx4 v[60:63], v5, s[10:11] offset:16
	global_load_dwordx4 v[64:67], v6, s[10:11]
	global_load_dwordx4 v[68:71], v6, s[10:11] offset:16
	v_add_u32_e32 v0, 256, v183
	v_mul_u32_u24_e32 v1, 0x925, v0
	v_lshrrev_b32_e32 v1, 18, v1
	v_mul_u32_u24_e32 v2, 0x70, v1
	v_sub_u32_e32 v2, v0, v2
	v_cmp_gt_u32_e32 vcc, 64, v2
	v_mov_b32_e32 v3, 0x1140
	v_mov_b32_e32 v4, 0x900
	v_cndmask_b32_e32 v3, v3, v4, vcc
	v_lshl_add_u32 v3, v2, 4, v3
	v_mul_u32_u24_e32 v4, 0x1980, v1
	v_add_u32_e32 v155, v3, v4
	global_load_dwordx4 v[44:47], v155, s[18:19]
	v_and_b32_e32 v5, 3, v2
	v_lshlrev_b32_e32 v5, 5, v5
	v_and_b32_e32 v6, 32, v2
	v_lshl_add_u32 v5, v6, 2, v5
	v_add_u32_e32 v5, s99, v5
	v_subrev_u32_e32 v6, 64, v2
	v_and_b32_e32 v7, 7, v6
	v_lshlrev_b32_e32 v7, 5, v7
	v_and_b32_e32 v8, 32, v6
	v_lshl_add_u32 v7, v8, 3, v7
	v_lshl_add_u32 v7, s99, 1, v7
	v_cndmask_b32_e32 v12, v7, v5, vcc
	v_mov_b32_e32 v8, s8
	v_mov_b32_e32 v9, s9
	v_mov_b32_e32 v10, s6
	v_mov_b32_e32 v11, s7
	v_cndmask_b32_e32 v8, v8, v10, vcc
	v_cndmask_b32_e32 v9, v9, v11, vcc
	v_mov_b32_e32 v13, 0
	v_lshl_add_u64 v[8:9], v[8:9], 0, v[12:13]
	global_load_dwordx4 v[128:131], v[8:9], off
	global_load_dwordx4 v[132:135], v[8:9], off offset:16
	v_and_b32_e32 v5, 1, v2
	v_and_b32_e32 v6, 3, v2
	v_cndmask_b32_e32 v5, v6, v5, vcc
	v_lshlrev_b32_e32 v5, 5, v5
	v_mov_b32_e32 v6, 0x80
	v_cndmask_b32_e64 v6, v6, 0, vcc
	v_add_u32_e32 v5, v5, v6
	v_mul_u32_u24_e32 v6, 0x180, v1
	v_add_u32_e32 v5, v5, v6
	v_mov_b32_e32 v6, 0x80
	v_mov_b32_e32 v7, 0x40
	v_cndmask_b32_e32 v6, v6, v7, vcc
	v_add_u32_e32 v6, v5, v6
	global_load_dwordx4 v[72:75], v5, s[10:11]
	global_load_dwordx4 v[76:79], v5, s[10:11] offset:16
	global_load_dwordx4 v[80:83], v6, s[10:11]
	global_load_dwordx4 v[84:87], v6, s[10:11] offset:16
	v_add_u32_e32 v0, 512, v183
	v_mul_u32_u24_e32 v1, 0x925, v0
	v_lshrrev_b32_e32 v1, 18, v1
	v_mul_u32_u24_e32 v2, 0x70, v1
	v_sub_u32_e32 v2, v0, v2
	v_cmp_gt_u32_e32 vcc, 64, v2
	v_mov_b32_e32 v3, 0x1140
	v_mov_b32_e32 v4, 0x900
	v_cndmask_b32_e32 v3, v3, v4, vcc
	v_lshl_add_u32 v3, v2, 4, v3
	v_mul_u32_u24_e32 v4, 0x1980, v1
	v_add_u32_e32 v156, v3, v4
	global_load_dwordx4 v[48:51], v156, s[18:19]
	v_and_b32_e32 v5, 3, v2
	v_lshlrev_b32_e32 v5, 5, v5
	v_and_b32_e32 v6, 32, v2
	v_lshl_add_u32 v5, v6, 2, v5
	v_add_u32_e32 v5, s99, v5
	v_subrev_u32_e32 v6, 64, v2
	v_and_b32_e32 v7, 7, v6
	v_lshlrev_b32_e32 v7, 5, v7
	v_and_b32_e32 v8, 32, v6
	v_lshl_add_u32 v7, v8, 3, v7
	v_lshl_add_u32 v7, s99, 1, v7
	v_cndmask_b32_e32 v12, v7, v5, vcc
	v_mov_b32_e32 v8, s8
	v_mov_b32_e32 v9, s9
	v_mov_b32_e32 v10, s6
	v_mov_b32_e32 v11, s7
	v_cndmask_b32_e32 v8, v8, v10, vcc
	v_cndmask_b32_e32 v9, v9, v11, vcc
	v_mov_b32_e32 v13, 0
	v_lshl_add_u64 v[8:9], v[8:9], 0, v[12:13]
	global_load_dwordx4 v[136:139], v[8:9], off
	global_load_dwordx4 v[140:143], v[8:9], off offset:16
	v_and_b32_e32 v5, 1, v2
	v_and_b32_e32 v6, 3, v2
	v_cndmask_b32_e32 v5, v6, v5, vcc
	v_lshlrev_b32_e32 v5, 5, v5
	v_mov_b32_e32 v6, 0x80
	v_cndmask_b32_e64 v6, v6, 0, vcc
	v_add_u32_e32 v5, v5, v6
	v_mul_u32_u24_e32 v6, 0x180, v1
	v_add_u32_e32 v5, v5, v6
	v_mov_b32_e32 v6, 0x80
	v_mov_b32_e32 v7, 0x40
	v_cndmask_b32_e32 v6, v6, v7, vcc
	v_add_u32_e32 v6, v5, v6
	global_load_dwordx4 v[88:91], v5, s[10:11]
	global_load_dwordx4 v[92:95], v5, s[10:11] offset:16
	global_load_dwordx4 v[96:99], v6, s[10:11]
	global_load_dwordx4 v[100:103], v6, s[10:11] offset:16
	v_add_u32_e32 v0, 768, v183
	v_mul_u32_u24_e32 v1, 0x925, v0
	v_lshrrev_b32_e32 v1, 18, v1
	v_mul_u32_u24_e32 v2, 0x70, v1
	v_sub_u32_e32 v2, v0, v2
	v_cmp_gt_u32_e32 vcc, 64, v2
	v_mov_b32_e32 v3, 0x1140
	v_mov_b32_e32 v4, 0x900
	v_cndmask_b32_e32 v3, v3, v4, vcc
	v_lshl_add_u32 v3, v2, 4, v3
	v_mul_u32_u24_e32 v4, 0x1980, v1
	v_add_u32_e32 v157, v3, v4
	global_load_dwordx4 v[52:55], v157, s[18:19]
	v_and_b32_e32 v5, 3, v2
	v_lshlrev_b32_e32 v5, 5, v5
	v_and_b32_e32 v6, 32, v2
	v_lshl_add_u32 v5, v6, 2, v5
	v_add_u32_e32 v5, s99, v5
	v_subrev_u32_e32 v6, 64, v2
	v_and_b32_e32 v7, 7, v6
	v_lshlrev_b32_e32 v7, 5, v7
	v_and_b32_e32 v8, 32, v6
	v_lshl_add_u32 v7, v8, 3, v7
	v_lshl_add_u32 v7, s99, 1, v7
	v_cndmask_b32_e32 v12, v7, v5, vcc
	v_mov_b32_e32 v8, s8
	v_mov_b32_e32 v9, s9
	v_mov_b32_e32 v10, s6
	v_mov_b32_e32 v11, s7
	v_cndmask_b32_e32 v8, v8, v10, vcc
	v_cndmask_b32_e32 v9, v9, v11, vcc
	v_mov_b32_e32 v13, 0
	v_lshl_add_u64 v[8:9], v[8:9], 0, v[12:13]
	global_load_dwordx4 v[144:147], v[8:9], off
	global_load_dwordx4 v[148:151], v[8:9], off offset:16
	v_and_b32_e32 v5, 1, v2
	v_and_b32_e32 v6, 3, v2
	v_cndmask_b32_e32 v5, v6, v5, vcc
	v_lshlrev_b32_e32 v5, 5, v5
	v_mov_b32_e32 v6, 0x80
	v_cndmask_b32_e64 v6, v6, 0, vcc
	v_add_u32_e32 v5, v5, v6
	v_mul_u32_u24_e32 v6, 0x180, v1
	v_add_u32_e32 v5, v5, v6
	v_mov_b32_e32 v6, 0x80
	v_mov_b32_e32 v7, 0x40
	v_cndmask_b32_e32 v6, v6, v7, vcc
	v_add_u32_e32 v6, v5, v6
	global_load_dwordx4 v[104:107], v5, s[10:11]
	global_load_dwordx4 v[108:111], v5, s[10:11] offset:16
	global_load_dwordx4 v[112:115], v6, s[10:11]
	global_load_dwordx4 v[116:119], v6, s[10:11] offset:16
	s_lshl_b32 s24, s20, 3
	s_and_saveexec_b64 s[8:9], s[2:3]
	s_cbranch_execz .LBB0_309
	s_mov_b64 s[10:11], 0
	v_mov_b32_e32 v28, v31
	v_mov_b32_e32 v30, v29
	s_branch .LBB0_271

; DI int oidx(int i) { asm volatile("" : "+s"(i)); return i; }
; DN void phase_prep(const Params& p, int l, char* smem) {
;     ...
;       unpack8(*(const u32x4*)ptr, x);
;       load8f(da ? (p.in[oidx(21)] + (l * 2 + (isq ? 0 : 1)) * 32 + dofs) : (p.in[oidx(27)] + (l * 2 + (isq ? 0 : 1)) * 64 + dofs), gs);
;       float ss = 0.f;
; #pragma unroll
;       for (int e = 0; e < 8; ++e) ss += x[e] * x[e];
;       ss += dppf<0xB1>(ss); ss += dppf<0x4E>(ss);
;       const float ss8 = ss + dppf<0x141>(ss);
;       const float rstd = da ? rsqrtf(ss * (1.f / 32.f) + 1e-6f) : rsqrtf(ss8 * (1.f / 64.f) + 1e-6f);
;       float y[8];
; #pragma unroll
;       for (int e = 0; e < 8; ++e) y[e] = x[e] * rstd * gs[e];
;       float yp2[8], yp4[8];
; #pragma unroll
;       for (int e = 0; e < 8; ++e) { yp2[e] = __shfl_xor(y[e], 2); yp4[e] = __shfl_xor(y[e], 4); }
;       if (t < TL) {
;         const int idx0 = da ? ((gi & 1) * 8) : ((gq & 3) * 8);
;         const bool first = da ? ((gi & 2) == 0) : ((gq & 4) == 0);
;         float cs[8], sn[8];
;         load8f(rope + t * 96 + (da ? 0 : 32) + idx0, cs);
;         load8f(rope + t * 96 + (da ? 16 : 64) + idx0, sn);
; #pragma unroll
;         for (int e = 0; e < 8; ++e) {
;           const float yp = da ? yp2[e] : yp4[e];
;           y[e] = first ? (y[e] * cs[e] - yp * sn[e]) : (y[e] * cs[e] + yp * sn[e]);
;         }
;       }
.LBB0_309:
	s_or_b64 exec, exec, s[8:9]
	s_and_saveexec_b64 s[16:17], s[4:5]
	s_cbranch_execz .LBB0_267
	s_waitcnt vmcnt(21)
	v_mov_b32_e32 v0, v183
	v_mul_u32_u24_e32 v1, 0x925, v0
	v_lshrrev_b32_e32 v1, 18, v1
	v_mul_u32_u24_e32 v2, 0x70, v1
	v_sub_u32_e32 v2, v0, v2
	v_cmp_gt_u32_e64 s[6:7], 64, v2
	v_lshlrev_b32_e32 v8, 16, v40
	v_and_b32_e32 v9, 0xffff0000, v40
	v_lshlrev_b32_e32 v10, 16, v41
	v_and_b32_e32 v11, 0xffff0000, v41
	v_lshlrev_b32_e32 v12, 16, v42
	v_and_b32_e32 v13, 0xffff0000, v42
	v_lshlrev_b32_e32 v14, 16, v43
	v_and_b32_e32 v15, 0xffff0000, v43
	v_mul_f32_e32 v16, v8, v8
	v_fmac_f32_e32 v16, v9, v9
	v_fmac_f32_e32 v16, v10, v10
	v_fmac_f32_e32 v16, v11, v11
	v_fmac_f32_e32 v16, v12, v12
	v_fmac_f32_e32 v16, v13, v13
	v_fmac_f32_e32 v16, v14, v14
	v_fmac_f32_e32 v16, v15, v15
	s_nop 1
	v_add_f32_dpp v16, v16, v16 quad_perm:[1,0,3,2] row_mask:0xf bank_mask:0xf bound_ctrl:1
	s_nop 1
	v_add_f32_dpp v16, v16, v16 quad_perm:[2,3,0,1] row_mask:0xf bank_mask:0xf bound_ctrl:1
	s_nop 1
	v_add_f32_dpp v17, v16, v16 row_half_mirror row_mask:0xf bank_mask:0xf bound_ctrl:1
	v_mul_f32_e32 v16, 0x3d000000, v16
	v_mul_f32_e32 v17, 0x3c800000, v17
	v_cndmask_b32_e64 v16, v17, v16, s[6:7]
	v_add_f32_e32 v16, 0x358637bd, v16
	v_rsq_f32_e32 v16, v16
	s_nop 0
	v_mul_f32_e32 v8, v16, v8
	v_mul_f32_e32 v9, v16, v9
	v_mul_f32_e32 v10, v16, v10
	v_mul_f32_e32 v11, v16, v11
	v_mul_f32_e32 v12, v16, v12
	v_mul_f32_e32 v13, v16, v13
	v_mul_f32_e32 v14, v16, v14
	v_mul_f32_e32 v15, v16, v15
	v_mul_f32_e32 v8, v120, v8
	v_mul_f32_e32 v9, v121, v9
	v_mul_f32_e32 v10, v122, v10
	v_mul_f32_e32 v11, v123, v11
	v_mul_f32_e32 v12, v124, v12
	v_mul_f32_e32 v13, v125, v13
	v_mul_f32_e32 v14, v126, v14
	v_mul_f32_e32 v15, v127, v15
	s_cmp_eq_u32 s98, 1
	s_cbranch_scc1 .Lprep_norope_0
	v_and_b32_e32 v3, 2, v2
	v_and_b32_e32 v4, 4, v2
	v_lshlrev_b32_e32 v3, 1, v3
	v_cndmask_b32_e64 v3, v4, v3, s[6:7]
	v_lshlrev_b32_e32 v3, 29, v3
	v_xor_b32_e32 v3, 0x80000000, v3
	v_xor_b32_e32 v64, v3, v64
	v_xor_b32_e32 v65, v3, v65
	v_xor_b32_e32 v66, v3, v66
	v_xor_b32_e32 v67, v3, v67
	v_xor_b32_e32 v68, v3, v68
	v_xor_b32_e32 v69, v3, v69
	v_xor_b32_e32 v70, v3, v70
	v_xor_b32_e32 v71, v3, v71
	v_mul_f32_dpp v17, v8, v64 quad_perm:[2,3,0,1] row_mask:0xf bank_mask:0xf bound_ctrl:1
	v_mul_f32_dpp v18, v9, v65 quad_perm:[2,3,0,1] row_mask:0xf bank_mask:0xf bound_ctrl:1
	v_mul_f32_dpp v19, v10, v66 quad_perm:[2,3,0,1] row_mask:0xf bank_mask:0xf bound_ctrl:1
	v_mul_f32_dpp v20, v11, v67 quad_perm:[2,3,0,1] row_mask:0xf bank_mask:0xf bound_ctrl:1
	v_mul_f32_dpp v21, v12, v68 quad_perm:[2,3,0,1] row_mask:0xf bank_mask:0xf bound_ctrl:1
	v_mul_f32_dpp v22, v13, v69 quad_perm:[2,3,0,1] row_mask:0xf bank_mask:0xf bound_ctrl:1
	v_mul_f32_dpp v23, v14, v70 quad_perm:[2,3,0,1] row_mask:0xf bank_mask:0xf bound_ctrl:1
	v_mul_f32_dpp v24, v15, v71 quad_perm:[2,3,0,1] row_mask:0xf bank_mask:0xf bound_ctrl:1
	v_mul_f32_dpp v32, v8, v64 row_ror:12 row_mask:0xf bank_mask:0x5 bound_ctrl:1
	v_mul_f32_dpp v32, v8, v64 row_ror:4 row_mask:0xf bank_mask:0xa bound_ctrl:1
	v_mul_f32_dpp v33, v9, v65 row_ror:12 row_mask:0xf bank_mask:0x5 bound_ctrl:1
	v_mul_f32_dpp v33, v9, v65 row_ror:4 row_mask:0xf bank_mask:0xa bound_ctrl:1
	v_mul_f32_dpp v34, v10, v66 row_ror:12 row_mask:0xf bank_mask:0x5 bound_ctrl:1
	v_mul_f32_dpp v34, v10, v66 row_ror:4 row_mask:0xf bank_mask:0xa bound_ctrl:1
	v_mul_f32_dpp v35, v11, v67 row_ror:12 row_mask:0xf bank_mask:0x5 bound_ctrl:1
	v_mul_f32_dpp v35, v11, v67 row_ror:4 row_mask:0xf bank_mask:0xa bound_ctrl:1
	v_mul_f32_dpp v36, v12, v68 row_ror:12 row_mask:0xf bank_mask:0x5 bound_ctrl:1
	v_mul_f32_dpp v36, v12, v68 row_ror:4 row_mask:0xf bank_mask:0xa bound_ctrl:1
	v_mul_f32_dpp v37, v13, v69 row_ror:12 row_mask:0xf bank_mask:0x5 bound_ctrl:1
	v_mul_f32_dpp v37, v13, v69 row_ror:4 row_mask:0xf bank_mask:0xa bound_ctrl:1
	v_mul_f32_dpp v38, v14, v70 row_ror:12 row_mask:0xf bank_mask:0x5 bound_ctrl:1
	v_mul_f32_dpp v38, v14, v70 row_ror:4 row_mask:0xf bank_mask:0xa bound_ctrl:1
	v_mul_f32_dpp v39, v15, v71 row_ror:12 row_mask:0xf bank_mask:0x5 bound_ctrl:1
	v_mul_f32_dpp v39, v15, v71 row_ror:4 row_mask:0xf bank_mask:0xa bound_ctrl:1
	v_cndmask_b32_e64 v17, v32, v17, s[6:7]
	v_cndmask_b32_e64 v18, v33, v18, s[6:7]
	v_cndmask_b32_e64 v19, v34, v19, s[6:7]
	v_cndmask_b32_e64 v20, v35, v20, s[6:7]
	v_cndmask_b32_e64 v21, v36, v21, s[6:7]
	v_cndmask_b32_e64 v22, v37, v22, s[6:7]
	v_cndmask_b32_e64 v23, v38, v23, s[6:7]
	v_cndmask_b32_e64 v24, v39, v24, s[6:7]
	v_fma_f32 v8, v8, v56, v17
	v_fma_f32 v9, v9, v57, v18
	v_fma_f32 v10, v10, v58, v19
	v_fma_f32 v11, v11, v59, v20
	v_fma_f32 v12, v12, v60, v21
	v_fma_f32 v13, v13, v61, v22
	v_fma_f32 v14, v14, v62, v23
	v_fma_f32 v15, v15, v63, v24
; DI unsigned pack2(float a, float b) { unsigned r; asm volatile("v_cvt_pk_bf16_f32 %0, %1, %2" : "=v"(r) : "v"(a), "v"(b)); return r; }
; DN void phase_prep(const Params& p, int l, char* smem) {
;     ...
;       float ss = 0.f;
; #pragma unroll
;       for (int e = 0; e < 8; ++e) ss += x[e] * x[e];
;       ss += dppf<0xB1>(ss); ss += dppf<0x4E>(ss);
;       const float ss8 = ss + dppf<0x141>(ss);
;       const float rstd = da ? rsqrtf(ss * (1.f / 32.f) + 1e-6f) : rsqrtf(ss8 * (1.f / 64.f) + 1e-6f);
;       float y[8];
; #pragma unroll
;       for (int e = 0; e < 8; ++e) y[e] = x[e] * rstd * gs[e];
;       float yp2[8], yp4[8];
; #pragma unroll
;       for (int e = 0; e < 8; ++e) { yp2[e] = __shfl_xor(y[e], 2); yp4[e] = __shfl_xor(y[e], 4); }
;       if (t < TL) {
;         const int idx0 = da ? ((gi & 1) * 8) : ((gq & 3) * 8);
;         const bool first = da ? ((gi & 2) == 0) : ((gq & 4) == 0);
;         float cs[8], sn[8];
;         load8f(rope + t * 96 + (da ? 0 : 32) + idx0, cs);
;         load8f(rope + t * 96 + (da ? 16 : 64) + idx0, sn);
; #pragma unroll
;         for (int e = 0; e < 8; ++e) {
;           const float yp = da ? yp2[e] : yp4[e];
;           y[e] = first ? (y[e] * cs[e] - yp * sn[e]) : (y[e] * cs[e] + yp * sn[e]);
;         }
;       }
;       const float qs = isq ? (da ? 0.25503486f : 0.18033688f) : 1.f;
;       u32x4 ow; ow.x = pack2(y[0] * qs, y[1] * qs); ow.y = pack2(y[2] * qs, y[3] * qs); ow.z = pack2(y[4] * qs, y[5] * qs); ow.w = pack2(y[6] * qs, y[7] * qs);
;       *(u32x4*)ptr = ow;
.Lprep_norope_0:
	v_mov_b32_e32 v3, 0x3e38aa3b
	v_mov_b32_e32 v4, 0x3e8293ee
	v_cndmask_b32_e64 v3, v3, v4, s[6:7]
	v_subrev_u32_e32 v4, 64, v2
	v_cndmask_b32_e64 v4, v4, v2, s[6:7]
	v_cmp_gt_u32_e32 vcc, 32, v4
	v_mov_b32_e32 v4, 1.0
	s_nop 0
	v_cndmask_b32_e32 v3, v4, v3, vcc
	v_mul_f32_e32 v8, v8, v3
	v_mul_f32_e32 v9, v9, v3
	v_mul_f32_e32 v10, v10, v3
	v_mul_f32_e32 v11, v11, v3
	v_mul_f32_e32 v12, v12, v3
	v_mul_f32_e32 v13, v13, v3
	v_mul_f32_e32 v14, v14, v3
	v_mul_f32_e32 v15, v15, v3
	v_cvt_pk_bf16_f32 v4, v8, v9
	v_cvt_pk_bf16_f32 v5, v10, v11
	v_cvt_pk_bf16_f32 v6, v12, v13
	v_cvt_pk_bf16_f32 v7, v14, v15
	global_store_dwordx4 v154, v[4:7], s[18:19]
	s_nop 1
	s_waitcnt vmcnt(15)
	v_add_u32_e32 v0, 256, v183
	v_mul_u32_u24_e32 v1, 0x925, v0
	v_lshrrev_b32_e32 v1, 18, v1
	v_mul_u32_u24_e32 v2, 0x70, v1
	v_sub_u32_e32 v2, v0, v2
	v_cmp_gt_u32_e64 s[6:7], 64, v2
	v_lshlrev_b32_e32 v8, 16, v44
	v_and_b32_e32 v9, 0xffff0000, v44
	v_lshlrev_b32_e32 v10, 16, v45
	v_and_b32_e32 v11, 0xffff0000, v45
	v_lshlrev_b32_e32 v12, 16, v46
	v_and_b32_e32 v13, 0xffff0000, v46
	v_lshlrev_b32_e32 v14, 16, v47
	v_and_b32_e32 v15, 0xffff0000, v47
	v_mul_f32_e32 v16, v8, v8
	v_fmac_f32_e32 v16, v9, v9
	v_fmac_f32_e32 v16, v10, v10
	v_fmac_f32_e32 v16, v11, v11
	v_fmac_f32_e32 v16, v12, v12
	v_fmac_f32_e32 v16, v13, v13
	v_fmac_f32_e32 v16, v14, v14
	v_fmac_f32_e32 v16, v15, v15
	s_nop 1
	v_add_f32_dpp v16, v16, v16 quad_perm:[1,0,3,2] row_mask:0xf bank_mask:0xf bound_ctrl:1
	s_nop 1
	v_add_f32_dpp v16, v16, v16 quad_perm:[2,3,0,1] row_mask:0xf bank_mask:0xf bound_ctrl:1
	s_nop 1
	v_add_f32_dpp v17, v16, v16 row_half_mirror row_mask:0xf bank_mask:0xf bound_ctrl:1
	v_mul_f32_e32 v16, 0x3d000000, v16
	v_mul_f32_e32 v17, 0x3c800000, v17
	v_cndmask_b32_e64 v16, v17, v16, s[6:7]
	v_add_f32_e32 v16, 0x358637bd, v16
	v_rsq_f32_e32 v16, v16
	s_nop 0
	v_mul_f32_e32 v8, v16, v8
	v_mul_f32_e32 v9, v16, v9
	v_mul_f32_e32 v10, v16, v10
	v_mul_f32_e32 v11, v16, v11
	v_mul_f32_e32 v12, v16, v12
	v_mul_f32_e32 v13, v16, v13
	v_mul_f32_e32 v14, v16, v14
	v_mul_f32_e32 v15, v16, v15
	v_mul_f32_e32 v8, v128, v8
	v_mul_f32_e32 v9, v129, v9
	v_mul_f32_e32 v10, v130, v10
	v_mul_f32_e32 v11, v131, v11
	v_mul_f32_e32 v12, v132, v12
	v_mul_f32_e32 v13, v133, v13
	v_mul_f32_e32 v14, v134, v14
	v_mul_f32_e32 v15, v135, v15
	s_cmp_eq_u32 s98, 1
	s_cbranch_scc1 .Lprep_norope_1
	v_and_b32_e32 v3, 2, v2
	v_and_b32_e32 v4, 4, v2
	v_lshlrev_b32_e32 v3, 1, v3
	v_cndmask_b32_e64 v3, v4, v3, s[6:7]
	v_lshlrev_b32_e32 v3, 29, v3
	v_xor_b32_e32 v3, 0x80000000, v3
	v_xor_b32_e32 v80, v3, v80
	v_xor_b32_e32 v81, v3, v81
	v_xor_b32_e32 v82, v3, v82
	v_xor_b32_e32 v83, v3, v83
	v_xor_b32_e32 v84, v3, v84
	v_xor_b32_e32 v85, v3, v85
	v_xor_b32_e32 v86, v3, v86
	v_xor_b32_e32 v87, v3, v87
	v_mul_f32_dpp v17, v8, v80 quad_perm:[2,3,0,1] row_mask:0xf bank_mask:0xf bound_ctrl:1
	v_mul_f32_dpp v18, v9, v81 quad_perm:[2,3,0,1] row_mask:0xf bank_mask:0xf bound_ctrl:1
	v_mul_f32_dpp v19, v10, v82 quad_perm:[2,3,0,1] row_mask:0xf bank_mask:0xf bound_ctrl:1
	v_mul_f32_dpp v20, v11, v83 quad_perm:[2,3,0,1] row_mask:0xf bank_mask:0xf bound_ctrl:1
	v_mul_f32_dpp v21, v12, v84 quad_perm:[2,3,0,1] row_mask:0xf bank_mask:0xf bound_ctrl:1
	v_mul_f32_dpp v22, v13, v85 quad_perm:[2,3,0,1] row_mask:0xf bank_mask:0xf bound_ctrl:1
	v_mul_f32_dpp v23, v14, v86 quad_perm:[2,3,0,1] row_mask:0xf bank_mask:0xf bound_ctrl:1
	v_mul_f32_dpp v24, v15, v87 quad_perm:[2,3,0,1] row_mask:0xf bank_mask:0xf bound_ctrl:1
	v_mul_f32_dpp v32, v8, v80 row_ror:12 row_mask:0xf bank_mask:0x5 bound_ctrl:1
	v_mul_f32_dpp v32, v8, v80 row_ror:4 row_mask:0xf bank_mask:0xa bound_ctrl:1
	v_mul_f32_dpp v33, v9, v81 row_ror:12 row_mask:0xf bank_mask:0x5 bound_ctrl:1
	v_mul_f32_dpp v33, v9, v81 row_ror:4 row_mask:0xf bank_mask:0xa bound_ctrl:1
	v_mul_f32_dpp v34, v10, v82 row_ror:12 row_mask:0xf bank_mask:0x5 bound_ctrl:1
	v_mul_f32_dpp v34, v10, v82 row_ror:4 row_mask:0xf bank_mask:0xa bound_ctrl:1
	v_mul_f32_dpp v35, v11, v83 row_ror:12 row_mask:0xf bank_mask:0x5 bound_ctrl:1
	v_mul_f32_dpp v35, v11, v83 row_ror:4 row_mask:0xf bank_mask:0xa bound_ctrl:1
	v_mul_f32_dpp v36, v12, v84 row_ror:12 row_mask:0xf bank_mask:0x5 bound_ctrl:1
	v_mul_f32_dpp v36, v12, v84 row_ror:4 row_mask:0xf bank_mask:0xa bound_ctrl:1
	v_mul_f32_dpp v37, v13, v85 row_ror:12 row_mask:0xf bank_mask:0x5 bound_ctrl:1
	v_mul_f32_dpp v37, v13, v85 row_ror:4 row_mask:0xf bank_mask:0xa bound_ctrl:1
	v_mul_f32_dpp v38, v14, v86 row_ror:12 row_mask:0xf bank_mask:0x5 bound_ctrl:1
	v_mul_f32_dpp v38, v14, v86 row_ror:4 row_mask:0xf bank_mask:0xa bound_ctrl:1
	v_mul_f32_dpp v39, v15, v87 row_ror:12 row_mask:0xf bank_mask:0x5 bound_ctrl:1
	v_mul_f32_dpp v39, v15, v87 row_ror:4 row_mask:0xf bank_mask:0xa bound_ctrl:1
	v_cndmask_b32_e64 v17, v32, v17, s[6:7]
	v_cndmask_b32_e64 v18, v33, v18, s[6:7]
	v_cndmask_b32_e64 v19, v34, v19, s[6:7]
	v_cndmask_b32_e64 v20, v35, v20, s[6:7]
	v_cndmask_b32_e64 v21, v36, v21, s[6:7]
	v_cndmask_b32_e64 v22, v37, v22, s[6:7]
	v_cndmask_b32_e64 v23, v38, v23, s[6:7]
	v_cndmask_b32_e64 v24, v39, v24, s[6:7]
	v_fma_f32 v8, v8, v72, v17
	v_fma_f32 v9, v9, v73, v18
	v_fma_f32 v10, v10, v74, v19
	v_fma_f32 v11, v11, v75, v20
	v_fma_f32 v12, v12, v76, v21
	v_fma_f32 v13, v13, v77, v22
	v_fma_f32 v14, v14, v78, v23
	v_fma_f32 v15, v15, v79, v24
; DI unsigned pack2(float a, float b) { unsigned r; asm volatile("v_cvt_pk_bf16_f32 %0, %1, %2" : "=v"(r) : "v"(a), "v"(b)); return r; }
; DN void phase_prep(const Params& p, int l, char* smem) {
;     ...
;       float ss = 0.f;
; #pragma unroll
;       for (int e = 0; e < 8; ++e) ss += x[e] * x[e];
;       ss += dppf<0xB1>(ss); ss += dppf<0x4E>(ss);
;       const float ss8 = ss + dppf<0x141>(ss);
;       const float rstd = da ? rsqrtf(ss * (1.f / 32.f) + 1e-6f) : rsqrtf(ss8 * (1.f / 64.f) + 1e-6f);
;       float y[8];
; #pragma unroll
;       for (int e = 0; e < 8; ++e) y[e] = x[e] * rstd * gs[e];
;       float yp2[8], yp4[8];
; #pragma unroll
;       for (int e = 0; e < 8; ++e) { yp2[e] = __shfl_xor(y[e], 2); yp4[e] = __shfl_xor(y[e], 4); }
;       if (t < TL) {
;         const int idx0 = da ? ((gi & 1) * 8) : ((gq & 3) * 8);
;         const bool first = da ? ((gi & 2) == 0) : ((gq & 4) == 0);
;         float cs[8], sn[8];
;         load8f(rope + t * 96 + (da ? 0 : 32) + idx0, cs);
;         load8f(rope + t * 96 + (da ? 16 : 64) + idx0, sn);
; #pragma unroll
;         for (int e = 0; e < 8; ++e) {
;           const float yp = da ? yp2[e] : yp4[e];
;           y[e] = first ? (y[e] * cs[e] - yp * sn[e]) : (y[e] * cs[e] + yp * sn[e]);
;         }
;       }
;       const float qs = isq ? (da ? 0.25503486f : 0.18033688f) : 1.f;
;       u32x4 ow; ow.x = pack2(y[0] * qs, y[1] * qs); ow.y = pack2(y[2] * qs, y[3] * qs); ow.z = pack2(y[4] * qs, y[5] * qs); ow.w = pack2(y[6] * qs, y[7] * qs);
;       *(u32x4*)ptr = ow;
.Lprep_norope_1:
	v_mov_b32_e32 v3, 0x3e38aa3b
	v_mov_b32_e32 v4, 0x3e8293ee
	v_cndmask_b32_e64 v3, v3, v4, s[6:7]
	v_subrev_u32_e32 v4, 64, v2
	v_cndmask_b32_e64 v4, v4, v2, s[6:7]
	v_cmp_gt_u32_e32 vcc, 32, v4
	v_mov_b32_e32 v4, 1.0
	s_nop 0
	v_cndmask_b32_e32 v3, v4, v3, vcc
	v_mul_f32_e32 v8, v8, v3
	v_mul_f32_e32 v9, v9, v3
	v_mul_f32_e32 v10, v10, v3
	v_mul_f32_e32 v11, v11, v3
	v_mul_f32_e32 v12, v12, v3
	v_mul_f32_e32 v13, v13, v3
	v_mul_f32_e32 v14, v14, v3
	v_mul_f32_e32 v15, v15, v3
	v_cvt_pk_bf16_f32 v4, v8, v9
	v_cvt_pk_bf16_f32 v5, v10, v11
	v_cvt_pk_bf16_f32 v6, v12, v13
	v_cvt_pk_bf16_f32 v7, v14, v15
	global_store_dwordx4 v155, v[4:7], s[18:19]
	s_nop 1
	s_waitcnt vmcnt(9)
	v_add_u32_e32 v0, 512, v183
	v_mul_u32_u24_e32 v1, 0x925, v0
	v_lshrrev_b32_e32 v1, 18, v1
	v_mul_u32_u24_e32 v2, 0x70, v1
	v_sub_u32_e32 v2, v0, v2
	v_cmp_gt_u32_e64 s[6:7], 64, v2
	v_lshlrev_b32_e32 v8, 16, v48
	v_and_b32_e32 v9, 0xffff0000, v48
	v_lshlrev_b32_e32 v10, 16, v49
	v_and_b32_e32 v11, 0xffff0000, v49
	v_lshlrev_b32_e32 v12, 16, v50
	v_and_b32_e32 v13, 0xffff0000, v50
	v_lshlrev_b32_e32 v14, 16, v51
	v_and_b32_e32 v15, 0xffff0000, v51
	v_mul_f32_e32 v16, v8, v8
	v_fmac_f32_e32 v16, v9, v9
	v_fmac_f32_e32 v16, v10, v10
	v_fmac_f32_e32 v16, v11, v11
	v_fmac_f32_e32 v16, v12, v12
	v_fmac_f32_e32 v16, v13, v13
	v_fmac_f32_e32 v16, v14, v14
	v_fmac_f32_e32 v16, v15, v15
	s_nop 1
	v_add_f32_dpp v16, v16, v16 quad_perm:[1,0,3,2] row_mask:0xf bank_mask:0xf bound_ctrl:1
	s_nop 1
	v_add_f32_dpp v16, v16, v16 quad_perm:[2,3,0,1] row_mask:0xf bank_mask:0xf bound_ctrl:1
	s_nop 1
	v_add_f32_dpp v17, v16, v16 row_half_mirror row_mask:0xf bank_mask:0xf bound_ctrl:1
	v_mul_f32_e32 v16, 0x3d000000, v16
	v_mul_f32_e32 v17, 0x3c800000, v17
	v_cndmask_b32_e64 v16, v17, v16, s[6:7]
	v_add_f32_e32 v16, 0x358637bd, v16
	v_rsq_f32_e32 v16, v16
	s_nop 0
	v_mul_f32_e32 v8, v16, v8
	v_mul_f32_e32 v9, v16, v9
	v_mul_f32_e32 v10, v16, v10
	v_mul_f32_e32 v11, v16, v11
	v_mul_f32_e32 v12, v16, v12
	v_mul_f32_e32 v13, v16, v13
	v_mul_f32_e32 v14, v16, v14
	v_mul_f32_e32 v15, v16, v15
	v_mul_f32_e32 v8, v136, v8
	v_mul_f32_e32 v9, v137, v9
	v_mul_f32_e32 v10, v138, v10
	v_mul_f32_e32 v11, v139, v11
	v_mul_f32_e32 v12, v140, v12
	v_mul_f32_e32 v13, v141, v13
	v_mul_f32_e32 v14, v142, v14
	v_mul_f32_e32 v15, v143, v15
	s_cmp_eq_u32 s98, 1
	s_cbranch_scc1 .Lprep_norope_2
	v_and_b32_e32 v3, 2, v2
	v_and_b32_e32 v4, 4, v2
	v_lshlrev_b32_e32 v3, 1, v3
	v_cndmask_b32_e64 v3, v4, v3, s[6:7]
	v_lshlrev_b32_e32 v3, 29, v3
	v_xor_b32_e32 v3, 0x80000000, v3
	v_xor_b32_e32 v96, v3, v96
	v_xor_b32_e32 v97, v3, v97
	v_xor_b32_e32 v98, v3, v98
	v_xor_b32_e32 v99, v3, v99
	v_xor_b32_e32 v100, v3, v100
	v_xor_b32_e32 v101, v3, v101
	v_xor_b32_e32 v102, v3, v102
	v_xor_b32_e32 v103, v3, v103
	v_mul_f32_dpp v17, v8, v96 quad_perm:[2,3,0,1] row_mask:0xf bank_mask:0xf bound_ctrl:1
	v_mul_f32_dpp v18, v9, v97 quad_perm:[2,3,0,1] row_mask:0xf bank_mask:0xf bound_ctrl:1
	v_mul_f32_dpp v19, v10, v98 quad_perm:[2,3,0,1] row_mask:0xf bank_mask:0xf bound_ctrl:1
	v_mul_f32_dpp v20, v11, v99 quad_perm:[2,3,0,1] row_mask:0xf bank_mask:0xf bound_ctrl:1
	v_mul_f32_dpp v21, v12, v100 quad_perm:[2,3,0,1] row_mask:0xf bank_mask:0xf bound_ctrl:1
	v_mul_f32_dpp v22, v13, v101 quad_perm:[2,3,0,1] row_mask:0xf bank_mask:0xf bound_ctrl:1
	v_mul_f32_dpp v23, v14, v102 quad_perm:[2,3,0,1] row_mask:0xf bank_mask:0xf bound_ctrl:1
	v_mul_f32_dpp v24, v15, v103 quad_perm:[2,3,0,1] row_mask:0xf bank_mask:0xf bound_ctrl:1
	v_mul_f32_dpp v32, v8, v96 row_ror:12 row_mask:0xf bank_mask:0x5 bound_ctrl:1
	v_mul_f32_dpp v32, v8, v96 row_ror:4 row_mask:0xf bank_mask:0xa bound_ctrl:1
	v_mul_f32_dpp v33, v9, v97 row_ror:12 row_mask:0xf bank_mask:0x5 bound_ctrl:1
	v_mul_f32_dpp v33, v9, v97 row_ror:4 row_mask:0xf bank_mask:0xa bound_ctrl:1
	v_mul_f32_dpp v34, v10, v98 row_ror:12 row_mask:0xf bank_mask:0x5 bound_ctrl:1
	v_mul_f32_dpp v34, v10, v98 row_ror:4 row_mask:0xf bank_mask:0xa bound_ctrl:1
	v_mul_f32_dpp v35, v11, v99 row_ror:12 row_mask:0xf bank_mask:0x5 bound_ctrl:1
	v_mul_f32_dpp v35, v11, v99 row_ror:4 row_mask:0xf bank_mask:0xa bound_ctrl:1
	v_mul_f32_dpp v36, v12, v100 row_ror:12 row_mask:0xf bank_mask:0x5 bound_ctrl:1
	v_mul_f32_dpp v36, v12, v100 row_ror:4 row_mask:0xf bank_mask:0xa bound_ctrl:1
	v_mul_f32_dpp v37, v13, v101 row_ror:12 row_mask:0xf bank_mask:0x5 bound_ctrl:1
	v_mul_f32_dpp v37, v13, v101 row_ror:4 row_mask:0xf bank_mask:0xa bound_ctrl:1
	v_mul_f32_dpp v38, v14, v102 row_ror:12 row_mask:0xf bank_mask:0x5 bound_ctrl:1
	v_mul_f32_dpp v38, v14, v102 row_ror:4 row_mask:0xf bank_mask:0xa bound_ctrl:1
	v_mul_f32_dpp v39, v15, v103 row_ror:12 row_mask:0xf bank_mask:0x5 bound_ctrl:1
	v_mul_f32_dpp v39, v15, v103 row_ror:4 row_mask:0xf bank_mask:0xa bound_ctrl:1
	v_cndmask_b32_e64 v17, v32, v17, s[6:7]
	v_cndmask_b32_e64 v18, v33, v18, s[6:7]
	v_cndmask_b32_e64 v19, v34, v19, s[6:7]
	v_cndmask_b32_e64 v20, v35, v20, s[6:7]
	v_cndmask_b32_e64 v21, v36, v21, s[6:7]
	v_cndmask_b32_e64 v22, v37, v22, s[6:7]
	v_cndmask_b32_e64 v23, v38, v23, s[6:7]
	v_cndmask_b32_e64 v24, v39, v24, s[6:7]
	v_fma_f32 v8, v8, v88, v17
	v_fma_f32 v9, v9, v89, v18
	v_fma_f32 v10, v10, v90, v19
	v_fma_f32 v11, v11, v91, v20
	v_fma_f32 v12, v12, v92, v21
	v_fma_f32 v13, v13, v93, v22
	v_fma_f32 v14, v14, v94, v23
	v_fma_f32 v15, v15, v95, v24
; DI unsigned pack2(float a, float b) { unsigned r; asm volatile("v_cvt_pk_bf16_f32 %0, %1, %2" : "=v"(r) : "v"(a), "v"(b)); return r; }
; DN void phase_prep(const Params& p, int l, char* smem) {
;     ...
;       float ss = 0.f;
; #pragma unroll
;       for (int e = 0; e < 8; ++e) ss += x[e] * x[e];
;       ss += dppf<0xB1>(ss); ss += dppf<0x4E>(ss);
;       const float ss8 = ss + dppf<0x141>(ss);
;       const float rstd = da ? rsqrtf(ss * (1.f / 32.f) + 1e-6f) : rsqrtf(ss8 * (1.f / 64.f) + 1e-6f);
;       float y[8];
; #pragma unroll
;       for (int e = 0; e < 8; ++e) y[e] = x[e] * rstd * gs[e];
;       float yp2[8], yp4[8];
; #pragma unroll
;       for (int e = 0; e < 8; ++e) { yp2[e] = __shfl_xor(y[e], 2); yp4[e] = __shfl_xor(y[e], 4); }
;       if (t < TL) {
;         const int idx0 = da ? ((gi & 1) * 8) : ((gq & 3) * 8);
;         const bool first = da ? ((gi & 2) == 0) : ((gq & 4) == 0);
;         float cs[8], sn[8];
;         load8f(rope + t * 96 + (da ? 0 : 32) + idx0, cs);
;         load8f(rope + t * 96 + (da ? 16 : 64) + idx0, sn);
; #pragma unroll
;         for (int e = 0; e < 8; ++e) {
;           const float yp = da ? yp2[e] : yp4[e];
;           y[e] = first ? (y[e] * cs[e] - yp * sn[e]) : (y[e] * cs[e] + yp * sn[e]);
;         }
;       }
;       const float qs = isq ? (da ? 0.25503486f : 0.18033688f) : 1.f;
;       u32x4 ow; ow.x = pack2(y[0] * qs, y[1] * qs); ow.y = pack2(y[2] * qs, y[3] * qs); ow.z = pack2(y[4] * qs, y[5] * qs); ow.w = pack2(y[6] * qs, y[7] * qs);
;       *(u32x4*)ptr = ow;
.Lprep_norope_2:
	v_mov_b32_e32 v3, 0x3e38aa3b
	v_mov_b32_e32 v4, 0x3e8293ee
	v_cndmask_b32_e64 v3, v3, v4, s[6:7]
	v_subrev_u32_e32 v4, 64, v2
	v_cndmask_b32_e64 v4, v4, v2, s[6:7]
	v_cmp_gt_u32_e32 vcc, 32, v4
	v_mov_b32_e32 v4, 1.0
	s_nop 0
	v_cndmask_b32_e32 v3, v4, v3, vcc
	v_mul_f32_e32 v8, v8, v3
	v_mul_f32_e32 v9, v9, v3
	v_mul_f32_e32 v10, v10, v3
	v_mul_f32_e32 v11, v11, v3
	v_mul_f32_e32 v12, v12, v3
	v_mul_f32_e32 v13, v13, v3
	v_mul_f32_e32 v14, v14, v3
	v_mul_f32_e32 v15, v15, v3
	v_cvt_pk_bf16_f32 v4, v8, v9
	v_cvt_pk_bf16_f32 v5, v10, v11
	v_cvt_pk_bf16_f32 v6, v12, v13
	v_cvt_pk_bf16_f32 v7, v14, v15
	global_store_dwordx4 v156, v[4:7], s[18:19]
	s_nop 1
	s_waitcnt vmcnt(3)
	v_add_u32_e32 v0, 768, v183
	v_mul_u32_u24_e32 v1, 0x925, v0
	v_lshrrev_b32_e32 v1, 18, v1
	v_mul_u32_u24_e32 v2, 0x70, v1
	v_sub_u32_e32 v2, v0, v2
	v_cmp_gt_u32_e64 s[6:7], 64, v2
	v_lshlrev_b32_e32 v8, 16, v52
	v_and_b32_e32 v9, 0xffff0000, v52
	v_lshlrev_b32_e32 v10, 16, v53
	v_and_b32_e32 v11, 0xffff0000, v53
	v_lshlrev_b32_e32 v12, 16, v54
	v_and_b32_e32 v13, 0xffff0000, v54
	v_lshlrev_b32_e32 v14, 16, v55
	v_and_b32_e32 v15, 0xffff0000, v55
	v_mul_f32_e32 v16, v8, v8
	v_fmac_f32_e32 v16, v9, v9
	v_fmac_f32_e32 v16, v10, v10
	v_fmac_f32_e32 v16, v11, v11
	v_fmac_f32_e32 v16, v12, v12
	v_fmac_f32_e32 v16, v13, v13
	v_fmac_f32_e32 v16, v14, v14
	v_fmac_f32_e32 v16, v15, v15
	s_nop 1
	v_add_f32_dpp v16, v16, v16 quad_perm:[1,0,3,2] row_mask:0xf bank_mask:0xf bound_ctrl:1
	s_nop 1
	v_add_f32_dpp v16, v16, v16 quad_perm:[2,3,0,1] row_mask:0xf bank_mask:0xf bound_ctrl:1
	s_nop 1
	v_add_f32_dpp v17, v16, v16 row_half_mirror row_mask:0xf bank_mask:0xf bound_ctrl:1
	v_mul_f32_e32 v16, 0x3d000000, v16
	v_mul_f32_e32 v17, 0x3c800000, v17
	v_cndmask_b32_e64 v16, v17, v16, s[6:7]
	v_add_f32_e32 v16, 0x358637bd, v16
	v_rsq_f32_e32 v16, v16
	s_nop 0
	v_mul_f32_e32 v8, v16, v8
	v_mul_f32_e32 v9, v16, v9
	v_mul_f32_e32 v10, v16, v10
	v_mul_f32_e32 v11, v16, v11
	v_mul_f32_e32 v12, v16, v12
	v_mul_f32_e32 v13, v16, v13
	v_mul_f32_e32 v14, v16, v14
	v_mul_f32_e32 v15, v16, v15
	v_mul_f32_e32 v8, v144, v8
	v_mul_f32_e32 v9, v145, v9
	v_mul_f32_e32 v10, v146, v10
	v_mul_f32_e32 v11, v147, v11
	v_mul_f32_e32 v12, v148, v12
	v_mul_f32_e32 v13, v149, v13
	v_mul_f32_e32 v14, v150, v14
	v_mul_f32_e32 v15, v151, v15
	s_cmp_eq_u32 s98, 1
	s_cbranch_scc1 .Lprep_norope_3
	v_and_b32_e32 v3, 2, v2
	v_and_b32_e32 v4, 4, v2
	v_lshlrev_b32_e32 v3, 1, v3
	v_cndmask_b32_e64 v3, v4, v3, s[6:7]
	v_lshlrev_b32_e32 v3, 29, v3
	v_xor_b32_e32 v3, 0x80000000, v3
	v_xor_b32_e32 v112, v3, v112
	v_xor_b32_e32 v113, v3, v113
	v_xor_b32_e32 v114, v3, v114
	v_xor_b32_e32 v115, v3, v115
	v_xor_b32_e32 v116, v3, v116
	v_xor_b32_e32 v117, v3, v117
	v_xor_b32_e32 v118, v3, v118
	v_xor_b32_e32 v119, v3, v119
	v_mul_f32_dpp v17, v8, v112 quad_perm:[2,3,0,1] row_mask:0xf bank_mask:0xf bound_ctrl:1
	v_mul_f32_dpp v18, v9, v113 quad_perm:[2,3,0,1] row_mask:0xf bank_mask:0xf bound_ctrl:1
	v_mul_f32_dpp v19, v10, v114 quad_perm:[2,3,0,1] row_mask:0xf bank_mask:0xf bound_ctrl:1
	v_mul_f32_dpp v20, v11, v115 quad_perm:[2,3,0,1] row_mask:0xf bank_mask:0xf bound_ctrl:1
	v_mul_f32_dpp v21, v12, v116 quad_perm:[2,3,0,1] row_mask:0xf bank_mask:0xf bound_ctrl:1
	v_mul_f32_dpp v22, v13, v117 quad_perm:[2,3,0,1] row_mask:0xf bank_mask:0xf bound_ctrl:1
	v_mul_f32_dpp v23, v14, v118 quad_perm:[2,3,0,1] row_mask:0xf bank_mask:0xf bound_ctrl:1
	v_mul_f32_dpp v24, v15, v119 quad_perm:[2,3,0,1] row_mask:0xf bank_mask:0xf bound_ctrl:1
	v_mul_f32_dpp v32, v8, v112 row_ror:12 row_mask:0xf bank_mask:0x5 bound_ctrl:1
	v_mul_f32_dpp v32, v8, v112 row_ror:4 row_mask:0xf bank_mask:0xa bound_ctrl:1
	v_mul_f32_dpp v33, v9, v113 row_ror:12 row_mask:0xf bank_mask:0x5 bound_ctrl:1
	v_mul_f32_dpp v33, v9, v113 row_ror:4 row_mask:0xf bank_mask:0xa bound_ctrl:1
	v_mul_f32_dpp v34, v10, v114 row_ror:12 row_mask:0xf bank_mask:0x5 bound_ctrl:1
	v_mul_f32_dpp v34, v10, v114 row_ror:4 row_mask:0xf bank_mask:0xa bound_ctrl:1
	v_mul_f32_dpp v35, v11, v115 row_ror:12 row_mask:0xf bank_mask:0x5 bound_ctrl:1
	v_mul_f32_dpp v35, v11, v115 row_ror:4 row_mask:0xf bank_mask:0xa bound_ctrl:1
	v_mul_f32_dpp v36, v12, v116 row_ror:12 row_mask:0xf bank_mask:0x5 bound_ctrl:1
	v_mul_f32_dpp v36, v12, v116 row_ror:4 row_mask:0xf bank_mask:0xa bound_ctrl:1
	v_mul_f32_dpp v37, v13, v117 row_ror:12 row_mask:0xf bank_mask:0x5 bound_ctrl:1
	v_mul_f32_dpp v37, v13, v117 row_ror:4 row_mask:0xf bank_mask:0xa bound_ctrl:1
	v_mul_f32_dpp v38, v14, v118 row_ror:12 row_mask:0xf bank_mask:0x5 bound_ctrl:1
	v_mul_f32_dpp v38, v14, v118 row_ror:4 row_mask:0xf bank_mask:0xa bound_ctrl:1
	v_mul_f32_dpp v39, v15, v119 row_ror:12 row_mask:0xf bank_mask:0x5 bound_ctrl:1
	v_mul_f32_dpp v39, v15, v119 row_ror:4 row_mask:0xf bank_mask:0xa bound_ctrl:1
	v_cndmask_b32_e64 v17, v32, v17, s[6:7]
	v_cndmask_b32_e64 v18, v33, v18, s[6:7]
	v_cndmask_b32_e64 v19, v34, v19, s[6:7]
	v_cndmask_b32_e64 v20, v35, v20, s[6:7]
	v_cndmask_b32_e64 v21, v36, v21, s[6:7]
	v_cndmask_b32_e64 v22, v37, v22, s[6:7]
	v_cndmask_b32_e64 v23, v38, v23, s[6:7]
	v_cndmask_b32_e64 v24, v39, v24, s[6:7]
	v_fma_f32 v8, v8, v104, v17
	v_fma_f32 v9, v9, v105, v18
	v_fma_f32 v10, v10, v106, v19
	v_fma_f32 v11, v11, v107, v20
	v_fma_f32 v12, v12, v108, v21
	v_fma_f32 v13, v13, v109, v22
	v_fma_f32 v14, v14, v110, v23
	v_fma_f32 v15, v15, v111, v24
